# attention units: the first unit of each kind no longer drains its Q loads before the pre-DMA barrier; the first K-tile wait (issued later, retires in order) covers them
# speedup vs baseline: 1.0024x; 1.0024x over previous
; template <int DV, int NMAP>
; __device__ __forceinline__ void attn_unit(LAS unsigned char* lds, const bf16_t* U, bf16_t* MIX, const float* logf, int b, int h, int qb, float lam, float slope2, const float* gn, float outscale, const int tid) {
;     ...
;     bf16x8 qr[4];
;     {
;         const bf16_t* qp = U + (rowbase + qrow0 + r32) * UW + qcol + map * 64 + hi * 8;
; #pragma unroll
;         for (int d0 = 0; d0 < 4; ++d0) qr[d0] = *(const bf16x8*)(qp + 16 * d0);
;     }
;     asm volatile("" : "+v"(qr[0]), "+v"(qr[1]), "+v"(qr[2]), "+v"(qr[3]));
;     const bf16_t* kg = U + (rowbase + lane) * UW + kcol + wid * 8;
;     const bf16_t* vg = U + (rowbase + 16 * (wid & 3) + (lane >> 2)) * UW + vcol + (wid >> 2) * 32 + (lane & 3) * 8;
;     const unsigned ldsb = (unsigned)(size_t)lds;
;     ...
;     __syncthreads();
;     AT_DMA(0, 0);
;     if (NT > 1) AT_DMA(1, 1);
;     const float m_run = bias[qrow0 + r32];
.Lfx_bias_done:
	s_lshl_b32 s36, s40, 5
	s_add_i32 s36, s36, s33
	s_lshr_b32 s37, s37, 6
	s_lshl_b32 s33, s60, 6
	s_ashr_i32 s30, s36, 31
	s_add_u32 s31, s36, s20
	v_or_b32_e32 v98, s31, v122
	v_mov_b64_e32 v[2:3], s[84:85]
	s_addc_u32 s61, s30, 0
	v_mad_u64_u32 v[2:3], s[30:31], v98, s87, v[2:3]
	v_mov_b32_e32 v0, 0x1800
	v_mad_i32_i24 v3, s61, v0, v3
	s_lshl_b32 s30, s60, 7
	s_mov_b32 s31, s21
	v_lshl_add_u64 v[2:3], v[2:3], 0, s[30:31]
	v_lshlrev_b32_e32 v0, 1, v126
	v_lshl_add_u64 v[2:3], v[2:3], 0, v[0:1]
	global_load_dwordx4 v[66:69], v[2:3], off offset:96
	global_load_dwordx4 v[70:73], v[2:3], off offset:64
	global_load_dwordx4 v[74:77], v[2:3], off offset:32
	global_load_dwordx4 v[78:81], v[2:3], off
	v_or_b32_e32 v0, s20, v123
	v_mul_u32_u24_e32 v0, 0xc00, v0
	v_lshlrev_b32_e32 v0, 1, v0
	v_lshl_add_u64 v[2:3], s[84:85], 0, v[0:1]
	s_lshl_b32 s60, s40, 3
	v_mov_b32_e32 v99, s61
	v_lshl_add_u64 v[2:3], v[2:3], 0, s[30:31]
	s_ashr_i32 s61, s60, 31
	v_lshl_add_u64 v[2:3], s[60:61], 1, v[2:3]
	s_mov_b64 s[60:61], 0x400
	v_lshl_add_u64 v[4:5], v[2:3], 0, s[60:61]
	s_bfe_u32 s60, s41, 0x20006
	v_lshl_or_b32 v0, s60, 4, v127
	v_or_b32_e32 v0, s20, v0
	v_mul_u32_u24_e32 v0, 0xc00, v0
	v_lshlrev_b32_e32 v0, 1, v0
	v_lshl_add_u64 v[6:7], s[84:85], 0, v[0:1]
	s_ashr_i32 s41, s41, 8
	v_lshl_add_u64 v[6:7], v[6:7], 0, s[30:31]
	s_lshl_b32 s30, s41, 5
	s_ashr_i32 s31, s30, 31
	s_mul_i32 s61, s40, 0x420
	v_lshl_add_u64 v[6:7], s[30:31], 1, v[6:7]
	s_add_i32 s20, s61, s49
	s_lshl_b32 s31, s60, 10
	v_lshlrev_b32_e32 v0, 1, v128
	v_lshl_add_u64 v[6:7], v[6:7], 0, v[0:1]
	v_lshl_add_u64 v[8:9], v[6:7], 0, s[50:51]
	v_or_b32_e32 v0, s36, v122
	v_mov_b32_e32 v105, 0
	s_or_b32 s60, s36, 31
	s_mov_b32 s64, 0
	v_mov_b32_e32 v106, v142
	s_mov_b32 s62, 0
	v_mov_b32_e32 v10, v105
	v_mov_b32_e32 v11, v105
	v_mov_b32_e32 v12, v105
	v_mov_b32_e32 v13, v105
	v_mov_b32_e32 v14, v105
	v_mov_b32_e32 v15, v105
	v_mov_b32_e32 v16, v105
	v_mov_b32_e32 v17, v105
	v_mov_b32_e32 v18, 0
	v_mov_b32_e32 v19, v105
	v_mov_b32_e32 v20, v105
	v_mov_b32_e32 v21, v105
	v_mov_b32_e32 v22, v105
	v_mov_b32_e32 v23, v105
	v_mov_b32_e32 v24, v105
	v_mov_b32_e32 v25, v105
	v_mov_b32_e32 v26, v105
	v_mov_b32_e32 v27, v105
	v_mov_b32_e32 v28, v105
	v_mov_b32_e32 v29, v105
	v_mov_b32_e32 v30, v105
	v_mov_b32_e32 v31, v105
	v_mov_b32_e32 v32, v105
	v_mov_b32_e32 v33, v105
	v_readlane_b32 s30, v255, 20
	s_waitcnt lgkmcnt(0)
	s_cmp_eq_u32 s30, 4
	s_cbranch_scc1 .Lfx_u2
	s_barrier

; template <int DV, int NMAP>
; __device__ __forceinline__ void attn_unit(LAS unsigned char* lds, const bf16_t* U, bf16_t* MIX, const float* logf, int b, int h, int qb, float lam, float slope2, const float* gn, float outscale, const int tid) {
;     ...
;     bf16x8 qr[4];
;     {
;         const bf16_t* qp = U + (rowbase + qrow0 + r32) * UW + qcol + map * 64 + hi * 8;
; #pragma unroll
;         for (int d0 = 0; d0 < 4; ++d0) qr[d0] = *(const bf16x8*)(qp + 16 * d0);
;     }
;     asm volatile("" : "+v"(qr[0]), "+v"(qr[1]), "+v"(qr[2]), "+v"(qr[3]));
;     const bf16_t* kg = U + (rowbase + lane) * UW + kcol + wid * 8;
;     const bf16_t* vg = U + (rowbase + 16 * (wid & 3) + (lane >> 2)) * UW + vcol + (wid >> 2) * 32 + (lane & 3) * 8;
;     const unsigned ldsb = (unsigned)(size_t)lds;
;     ...
;     __syncthreads();
;     AT_DMA(0, 0);
;     if (NT > 1) AT_DMA(1, 1);
;     const float m_run = bias[qrow0 + r32];
.LBB0_217:
	s_or_b64 exec, exec, s[30:31]
	s_ashr_i32 s36, s33, 6
	s_and_b32 s61, s36, 3
	s_lshl_b32 s27, s27, 9
	s_lshl_b32 s30, s61, 5
	s_and_b32 s37, s27, 0x3800
	s_or_b32 s62, s30, s62
	v_or_b32_e32 v0, s37, v122
	v_or_b32_e32 v147, s62, v0
	v_mov_b64_e32 v[2:3], s[84:85]
	s_ashr_i32 s60, s33, 8
	v_mad_u64_u32 v[2:3], s[30:31], v147, s87, v[2:3]
	s_lshl_b32 s27, s20, 7
	s_lshl_b32 s20, s20, 8
	s_lshl_b32 s30, s60, 6
	v_lshl_add_u64 v[2:3], v[2:3], 0, s[20:21]
	s_ashr_i32 s31, s30, 31
	v_lshl_add_u64 v[2:3], s[30:31], 1, v[2:3]
	v_lshlrev_b32_e32 v0, 1, v126
	v_lshl_add_u64 v[2:3], v[2:3], 0, v[0:1]
	global_load_dwordx4 v[98:101], v[2:3], off offset:3168
	global_load_dwordx4 v[102:105], v[2:3], off offset:3136
	global_load_dwordx4 v[106:109], v[2:3], off offset:3104
	global_load_dwordx4 v[110:113], v[2:3], off offset:3072
	v_or_b32_e32 v0, s37, v123
	v_mul_u32_u24_e32 v0, 0xc00, v0
	v_lshlrev_b32_e32 v0, 1, v0
	s_lshl_b32 s30, s36, 3
	v_lshl_add_u64 v[2:3], s[84:85], 0, v[0:1]
	s_ashr_i32 s31, s30, 31
	v_lshl_add_u64 v[2:3], v[2:3], 0, s[20:21]
	s_lshl_b64 s[40:41], s[30:31], 1
	s_mul_i32 s65, s36, 0x420
	v_lshl_add_u64 v[4:5], v[2:3], 0, s[40:41]
	v_lshl_or_b32 v2, s61, 4, v127
	s_add_i32 s67, s65, 0
	v_lshl_add_u64 v[6:7], v[4:5], 0, s[22:23]
	v_or_b32_e32 v2, s37, v2
	s_add_i32 s64, s67, 0x2100
	v_mul_u32_u24_e32 v2, 0xc00, v2
	v_lshlrev_b32_e32 v2, 1, v2
	v_mov_b32_e32 v3, v1
	s_lshl_b32 s30, s60, 5
	v_lshl_add_u64 v[8:9], s[84:85], 0, v[2:3]
	s_ashr_i32 s31, s30, 31
	v_lshl_add_u64 v[8:9], v[8:9], 0, s[20:21]
	s_lshr_b32 s63, s63, 6
	v_or_b32_e32 v148, s62, v122
	v_mov_b32_e32 v14, v1
	v_mov_b32_e32 v15, v1
	v_mov_b32_e32 v10, v1
	v_mov_b32_e32 v11, v1
	v_mov_b32_e32 v12, v1
	v_mov_b32_e32 v13, v1
	v_mov_b32_e32 v150, 0
	v_mov_b32_e32 v151, v142
	v_readlane_b32 s30, v255, 20
	s_nop 0
	s_cmp_eq_u32 s30, 2
	s_cbranch_scc1 .Ldf_u2
	s_waitcnt lgkmcnt(0)
	s_barrier
